# peel first K-iteration of in_proj/ffn_in/down GEMM loops: first MFMA per accumulator takes C=0, removing 128 v_mov zero-fills per unit
# speedup vs baseline: 1.0104x; 1.0085x over previous
.LBB0_211:
	s_ashr_i32 s41, s40, 31
	v_cmp_lt_i64_e32 vcc, s[8:9], v[160:161]
	s_lshl_b64 s[8:9], s[40:41], 19
	s_add_u32 s42, s47, s8
	s_addc_u32 s43, s48, s9
	s_and_b64 s[8:9], vcc, exec
	s_cselect_b32 s1, s43, s3
	s_cselect_b32 s33, s42, s2
	s_ashr_i32 s39, s38, 31
	s_lshl_b64 s[8:9], s[38:39], 19
	s_add_u32 s44, s94, s8
	s_addc_u32 s45, s95, s9
	s_and_b64 s[8:9], vcc, exec
	s_cselect_b32 s39, s45, s7
	s_cselect_b32 s41, s44, s6
	s_add_u32 s2, s2, 0x40080
	s_addc_u32 s3, s3, 0
	s_add_u32 s71, s6, 0x100
	s_addc_u32 s72, s7, 0
	s_mov_b32 s73, -2
	s_waitcnt vmcnt(0)
.Lpeel_p1:
	ds_read_b128 v[130:133], v173
	ds_read_b128 v[134:137], v173 offset:1024
	ds_read_b128 v[138:141], v173 offset:2048
	ds_read_b128 v[142:145], v173 offset:3072
	s_add_u32 s6, s2, 0xfffc0080
	s_addc_u32 s7, s3, -1
	s_cmp_eq_u32 s73, 12
	s_cselect_b32 s9, s1, s7
	s_cselect_b32 s8, s33, s6
	s_cselect_b32 s7, s39, s72
	s_cselect_b32 s6, s41, s71
	v_lshl_add_u64 v[214:215], s[2:3], 0, v[156:157]
	s_add_i32 m0, s50, 0xc000
	ds_read_b128 v[180:183], v175
	ds_read_b128 v[184:187], v175 offset:1024
	ds_read_b128 v[190:193], v175 offset:2048
	ds_read_b128 v[194:197], v175 offset:3072
	ds_read_b128 v[198:201], v175 offset:4096
	ds_read_b128 v[202:205], v175 offset:5120
	ds_read_b128 v[206:209], v175 offset:6144
	ds_read_b128 v[210:213], v175 offset:7168
	global_load_lds_dwordx4 v[214:215], off
	v_lshl_add_u64 v[214:215], s[2:3], 0, v[158:159]
	s_add_i32 m0, s50, 0xe000
	s_nop 0
	global_load_lds_dwordx4 v[214:215], off
	s_waitcnt lgkmcnt(8)
	s_barrier
	s_waitcnt lgkmcnt(0)
	s_setprio 1
	s_waitcnt lgkmcnt(0)
	v_mfma_f32_16x16x32_bf16 v[126:129], v[130:133], v[180:183], 0
	v_mfma_f32_16x16x32_bf16 v[122:125], v[138:141], v[180:183], 0
	v_mfma_f32_16x16x32_bf16 v[118:121], v[130:133], v[190:193], 0
	v_mfma_f32_16x16x32_bf16 v[110:113], v[138:141], v[190:193], 0
	v_mfma_f32_16x16x32_bf16 v[102:105], v[130:133], v[198:201], 0
	v_mfma_f32_16x16x32_bf16 v[94:97], v[138:141], v[198:201], 0
	v_mfma_f32_16x16x32_bf16 v[86:89], v[130:133], v[206:209], 0
	v_mfma_f32_16x16x32_bf16 v[78:81], v[138:141], v[206:209], 0
	v_mfma_f32_16x16x32_bf16 v[126:129], v[134:137], v[184:187], v[126:129]
	v_mfma_f32_16x16x32_bf16 v[122:125], v[142:145], v[184:187], v[122:125]
	v_mfma_f32_16x16x32_bf16 v[118:121], v[134:137], v[194:197], v[118:121]
	v_mfma_f32_16x16x32_bf16 v[110:113], v[142:145], v[194:197], v[110:113]
	v_mfma_f32_16x16x32_bf16 v[102:105], v[134:137], v[202:205], v[102:105]
	v_mfma_f32_16x16x32_bf16 v[94:97], v[142:145], v[202:205], v[94:97]
	v_mfma_f32_16x16x32_bf16 v[86:89], v[134:137], v[210:213], v[86:89]
	v_mfma_f32_16x16x32_bf16 v[78:81], v[142:145], v[210:213], v[78:81]
	s_setprio 0
	s_barrier
	s_add_i32 s74, s66, s49
	v_lshl_add_u64 v[230:231], s[6:7], 0, v[148:149]
	s_mov_b32 m0, s74
	ds_read_b128 v[214:217], v177
	ds_read_b128 v[218:221], v177 offset:1024
	ds_read_b128 v[222:225], v177 offset:2048
	ds_read_b128 v[226:229], v177 offset:3072
	global_load_lds_dwordx4 v[230:231], off
	v_lshl_add_u64 v[232:233], s[6:7], 0, v[152:153]
	s_add_i32 m0, s74, 0x2000
	s_nop 0
	global_load_lds_dwordx4 v[232:233], off
	s_barrier
	s_waitcnt lgkmcnt(0)
	s_setprio 1
	s_waitcnt lgkmcnt(0)
	v_mfma_f32_16x16x32_bf16 v[114:117], v[214:217], v[180:183], 0
	v_mfma_f32_16x16x32_bf16 v[106:109], v[222:225], v[180:183], 0
	v_mfma_f32_16x16x32_bf16 v[98:101], v[214:217], v[190:193], 0
	v_mfma_f32_16x16x32_bf16 v[90:93], v[222:225], v[190:193], 0
	v_mfma_f32_16x16x32_bf16 v[82:85], v[214:217], v[198:201], 0
	v_mfma_f32_16x16x32_bf16 v[74:77], v[222:225], v[198:201], 0
	v_mfma_f32_16x16x32_bf16 v[70:73], v[214:217], v[206:209], 0
	v_mfma_f32_16x16x32_bf16 v[66:69], v[222:225], v[206:209], 0
	v_mfma_f32_16x16x32_bf16 v[114:117], v[218:221], v[184:187], v[114:117]
	v_mfma_f32_16x16x32_bf16 v[106:109], v[226:229], v[184:187], v[106:109]
	v_mfma_f32_16x16x32_bf16 v[98:101], v[218:221], v[194:197], v[98:101]
	v_mfma_f32_16x16x32_bf16 v[90:93], v[226:229], v[194:197], v[90:93]
	v_mfma_f32_16x16x32_bf16 v[82:85], v[218:221], v[202:205], v[82:85]
	v_mfma_f32_16x16x32_bf16 v[74:77], v[226:229], v[202:205], v[74:77]
	v_mfma_f32_16x16x32_bf16 v[70:73], v[218:221], v[210:213], v[70:73]
	v_mfma_f32_16x16x32_bf16 v[66:69], v[226:229], v[210:213], v[66:69]
	s_setprio 0
	s_mov_b32 m0, s50
	v_lshl_add_u64 v[234:235], s[8:9], 0, v[146:147]
	s_barrier
	ds_read_b128 v[180:183], v175 offset:16384
	ds_read_b128 v[184:187], v175 offset:17408
	ds_read_b128 v[190:193], v175 offset:18432
	ds_read_b128 v[194:197], v175 offset:19456
	ds_read_b128 v[198:201], v175 offset:20480
	ds_read_b128 v[202:205], v175 offset:21504
	ds_read_b128 v[206:209], v175 offset:22528
	ds_read_b128 v[210:213], v175 offset:23552
	global_load_lds_dwordx4 v[234:235], off
	v_lshl_add_u64 v[236:237], s[8:9], 0, v[150:151]
	s_mov_b32 m0, s51
	s_nop 0
	global_load_lds_dwordx4 v[236:237], off
	s_barrier
	s_waitcnt lgkmcnt(0)
	s_setprio 1
	s_waitcnt lgkmcnt(0)
	v_mfma_f32_16x16x32_bf16 v[62:65], v[130:133], v[180:183], 0
	v_mfma_f32_16x16x32_bf16 v[58:61], v[138:141], v[180:183], 0
	v_mfma_f32_16x16x32_bf16 v[54:57], v[130:133], v[190:193], 0
	v_mfma_f32_16x16x32_bf16 v[46:49], v[138:141], v[190:193], 0
	v_mfma_f32_16x16x32_bf16 v[38:41], v[130:133], v[198:201], 0
	v_mfma_f32_16x16x32_bf16 v[30:33], v[138:141], v[198:201], 0
	v_mfma_f32_16x16x32_bf16 v[22:25], v[130:133], v[206:209], 0
	v_mfma_f32_16x16x32_bf16 v[14:17], v[138:141], v[206:209], 0
	v_mfma_f32_16x16x32_bf16 v[62:65], v[134:137], v[184:187], v[62:65]
	v_mfma_f32_16x16x32_bf16 v[58:61], v[142:145], v[184:187], v[58:61]
	v_mfma_f32_16x16x32_bf16 v[54:57], v[134:137], v[194:197], v[54:57]
	v_mfma_f32_16x16x32_bf16 v[46:49], v[142:145], v[194:197], v[46:49]
	v_mfma_f32_16x16x32_bf16 v[38:41], v[134:137], v[202:205], v[38:41]
	v_mfma_f32_16x16x32_bf16 v[30:33], v[142:145], v[202:205], v[30:33]
	v_mfma_f32_16x16x32_bf16 v[22:25], v[134:137], v[210:213], v[22:25]
	v_mfma_f32_16x16x32_bf16 v[14:17], v[142:145], v[210:213], v[14:17]
	s_setprio 0
	s_barrier
	s_add_u32 s74, s6, 0x40000
	s_addc_u32 s75, s7, 0
	s_add_i32 s76, s67, s49
	v_lshl_add_u64 v[130:131], s[74:75], 0, v[148:149]
	s_mov_b32 m0, s76
	s_nop 0
	global_load_lds_dwordx4 v[130:131], off
	v_lshl_add_u64 v[130:131], s[74:75], 0, v[152:153]
	s_add_i32 m0, s76, 0x2000
	s_nop 0
	global_load_lds_dwordx4 v[130:131], off
	s_waitcnt vmcnt(6)
	s_barrier
	s_setprio 1
	v_mfma_f32_16x16x32_bf16 v[50:53], v[214:217], v[180:183], 0
	v_mfma_f32_16x16x32_bf16 v[42:45], v[222:225], v[180:183], 0
	v_mfma_f32_16x16x32_bf16 v[34:37], v[214:217], v[190:193], 0
	v_mfma_f32_16x16x32_bf16 v[26:29], v[222:225], v[190:193], 0
	v_mfma_f32_16x16x32_bf16 v[18:21], v[214:217], v[198:201], 0
	v_mfma_f32_16x16x32_bf16 v[10:13], v[222:225], v[198:201], 0
	v_mfma_f32_16x16x32_bf16 v[6:9], v[214:217], v[206:209], 0
	v_mfma_f32_16x16x32_bf16 v[2:5], v[222:225], v[206:209], 0
	v_mfma_f32_16x16x32_bf16 v[50:53], v[218:221], v[184:187], v[50:53]
	v_mfma_f32_16x16x32_bf16 v[42:45], v[226:229], v[184:187], v[42:45]
	v_mfma_f32_16x16x32_bf16 v[34:37], v[218:221], v[194:197], v[34:37]
	v_mfma_f32_16x16x32_bf16 v[26:29], v[226:229], v[194:197], v[26:29]
	v_mfma_f32_16x16x32_bf16 v[18:21], v[218:221], v[202:205], v[18:21]
	v_mfma_f32_16x16x32_bf16 v[10:13], v[226:229], v[202:205], v[10:13]
	v_mfma_f32_16x16x32_bf16 v[6:9], v[218:221], v[210:213], v[6:9]
	v_mfma_f32_16x16x32_bf16 v[2:5], v[226:229], v[210:213], v[2:5]
	s_setprio 0
	s_add_i32 s74, 0, 0x18000
	v_add_u32_e32 v142, s74, v171
	s_barrier
	ds_read_b128 v[130:133], v142
	ds_read_b128 v[134:137], v142 offset:1024
	ds_read_b128 v[138:141], v142 offset:2048
	ds_read_b128 v[142:145], v142 offset:3072
	s_add_u32 s8, s8, 0x40000
	s_addc_u32 s9, s9, 0
	s_mov_b32 m0, s52
	v_lshl_add_u64 v[214:215], s[8:9], 0, v[146:147]
	ds_read_b128 v[180:183], v175 offset:32768
	ds_read_b128 v[184:187], v175 offset:33792
	ds_read_b128 v[190:193], v175 offset:34816
	ds_read_b128 v[194:197], v175 offset:35840
	ds_read_b128 v[198:201], v175 offset:36864
	ds_read_b128 v[202:205], v175 offset:37888
	ds_read_b128 v[206:209], v175 offset:38912
	ds_read_b128 v[210:213], v175 offset:39936
	global_load_lds_dwordx4 v[214:215], off
	v_lshl_add_u64 v[214:215], s[8:9], 0, v[150:151]
	s_mov_b32 m0, s53
	s_nop 0
	global_load_lds_dwordx4 v[214:215], off
	s_waitcnt lgkmcnt(8)
	s_barrier
	s_waitcnt lgkmcnt(0)
	s_setprio 1
	s_waitcnt lgkmcnt(0)
	v_mfma_f32_16x16x32_bf16 v[126:129], v[130:133], v[180:183], v[126:129]
	v_mfma_f32_16x16x32_bf16 v[122:125], v[138:141], v[180:183], v[122:125]
	v_mfma_f32_16x16x32_bf16 v[118:121], v[130:133], v[190:193], v[118:121]
	v_mfma_f32_16x16x32_bf16 v[110:113], v[138:141], v[190:193], v[110:113]
	v_mfma_f32_16x16x32_bf16 v[102:105], v[130:133], v[198:201], v[102:105]
	v_mfma_f32_16x16x32_bf16 v[94:97], v[138:141], v[198:201], v[94:97]
	v_mfma_f32_16x16x32_bf16 v[86:89], v[130:133], v[206:209], v[86:89]
	v_mfma_f32_16x16x32_bf16 v[78:81], v[138:141], v[206:209], v[78:81]
	v_mfma_f32_16x16x32_bf16 v[126:129], v[134:137], v[184:187], v[126:129]
	v_mfma_f32_16x16x32_bf16 v[122:125], v[142:145], v[184:187], v[122:125]
	v_mfma_f32_16x16x32_bf16 v[118:121], v[134:137], v[194:197], v[118:121]
	v_mfma_f32_16x16x32_bf16 v[110:113], v[142:145], v[194:197], v[110:113]
	v_mfma_f32_16x16x32_bf16 v[102:105], v[134:137], v[202:205], v[102:105]
	v_mfma_f32_16x16x32_bf16 v[94:97], v[142:145], v[202:205], v[94:97]
	v_mfma_f32_16x16x32_bf16 v[86:89], v[134:137], v[210:213], v[86:89]
	v_mfma_f32_16x16x32_bf16 v[78:81], v[142:145], v[210:213], v[78:81]
	s_setprio 0
	s_barrier
	s_add_i32 s8, 0, 0x1c000
	s_add_i32 s9, s74, s49
	v_add_u32_e32 v154, s8, v171
	v_lshl_add_u64 v[230:231], v[230:231], 0, s[26:27]
	s_mov_b32 m0, s9
	ds_read_b128 v[214:217], v154
	ds_read_b128 v[218:221], v154 offset:1024
	ds_read_b128 v[222:225], v154 offset:2048
	ds_read_b128 v[226:229], v154 offset:3072
	global_load_lds_dwordx4 v[230:231], off
	v_lshl_add_u64 v[230:231], v[232:233], 0, s[26:27]
	s_add_i32 m0, s9, 0x2000
	s_nop 0
	global_load_lds_dwordx4 v[230:231], off
	s_barrier
	s_waitcnt lgkmcnt(0)
	s_setprio 1
	s_waitcnt lgkmcnt(0)
	v_mfma_f32_16x16x32_bf16 v[114:117], v[214:217], v[180:183], v[114:117]
	v_mfma_f32_16x16x32_bf16 v[106:109], v[222:225], v[180:183], v[106:109]
	v_mfma_f32_16x16x32_bf16 v[98:101], v[214:217], v[190:193], v[98:101]
	v_mfma_f32_16x16x32_bf16 v[90:93], v[222:225], v[190:193], v[90:93]
	v_mfma_f32_16x16x32_bf16 v[82:85], v[214:217], v[198:201], v[82:85]
	v_mfma_f32_16x16x32_bf16 v[74:77], v[222:225], v[198:201], v[74:77]
	v_mfma_f32_16x16x32_bf16 v[70:73], v[214:217], v[206:209], v[70:73]
	v_mfma_f32_16x16x32_bf16 v[66:69], v[222:225], v[206:209], v[66:69]
	v_mfma_f32_16x16x32_bf16 v[114:117], v[218:221], v[184:187], v[114:117]
	v_mfma_f32_16x16x32_bf16 v[106:109], v[226:229], v[184:187], v[106:109]
	v_mfma_f32_16x16x32_bf16 v[98:101], v[218:221], v[194:197], v[98:101]
	v_mfma_f32_16x16x32_bf16 v[90:93], v[226:229], v[194:197], v[90:93]
	v_mfma_f32_16x16x32_bf16 v[82:85], v[218:221], v[202:205], v[82:85]
	v_mfma_f32_16x16x32_bf16 v[74:77], v[226:229], v[202:205], v[74:77]
	v_mfma_f32_16x16x32_bf16 v[70:73], v[218:221], v[210:213], v[70:73]
	v_mfma_f32_16x16x32_bf16 v[66:69], v[226:229], v[210:213], v[66:69]
	s_setprio 0
	s_mov_b32 m0, s56
	v_lshl_add_u64 v[230:231], v[234:235], 0, s[26:27]
	s_barrier
	ds_read_b128 v[180:183], v175 offset:49152
	ds_read_b128 v[184:187], v175 offset:50176
	ds_read_b128 v[190:193], v175 offset:51200
	ds_read_b128 v[194:197], v175 offset:52224
	ds_read_b128 v[198:201], v175 offset:53248
	ds_read_b128 v[202:205], v175 offset:54272
	ds_read_b128 v[206:209], v175 offset:55296
	ds_read_b128 v[210:213], v175 offset:56320
	global_load_lds_dwordx4 v[230:231], off
	v_lshl_add_u64 v[230:231], v[236:237], 0, s[26:27]
	s_mov_b32 m0, s57
	s_nop 0
	global_load_lds_dwordx4 v[230:231], off
	s_barrier
	s_waitcnt lgkmcnt(0)
	s_setprio 1
	s_waitcnt lgkmcnt(0)
	v_mfma_f32_16x16x32_bf16 v[62:65], v[130:133], v[180:183], v[62:65]
	v_mfma_f32_16x16x32_bf16 v[58:61], v[138:141], v[180:183], v[58:61]
	v_mfma_f32_16x16x32_bf16 v[54:57], v[130:133], v[190:193], v[54:57]
	v_mfma_f32_16x16x32_bf16 v[46:49], v[138:141], v[190:193], v[46:49]
	v_mfma_f32_16x16x32_bf16 v[38:41], v[130:133], v[198:201], v[38:41]
	v_mfma_f32_16x16x32_bf16 v[30:33], v[138:141], v[198:201], v[30:33]
	v_mfma_f32_16x16x32_bf16 v[22:25], v[130:133], v[206:209], v[22:25]
	v_mfma_f32_16x16x32_bf16 v[14:17], v[138:141], v[206:209], v[14:17]
	v_mfma_f32_16x16x32_bf16 v[62:65], v[134:137], v[184:187], v[62:65]
	v_mfma_f32_16x16x32_bf16 v[58:61], v[142:145], v[184:187], v[58:61]
	v_mfma_f32_16x16x32_bf16 v[54:57], v[134:137], v[194:197], v[54:57]
	v_mfma_f32_16x16x32_bf16 v[46:49], v[142:145], v[194:197], v[46:49]
	v_mfma_f32_16x16x32_bf16 v[38:41], v[134:137], v[202:205], v[38:41]
	v_mfma_f32_16x16x32_bf16 v[30:33], v[142:145], v[202:205], v[30:33]
	v_mfma_f32_16x16x32_bf16 v[22:25], v[134:137], v[210:213], v[22:25]
	v_mfma_f32_16x16x32_bf16 v[14:17], v[142:145], v[210:213], v[14:17]
	s_setprio 0
	s_barrier
	s_add_u32 s6, s6, 0x40080
	s_addc_u32 s7, s7, 0
	s_add_i32 s8, s8, s49
	v_lshl_add_u64 v[130:131], s[6:7], 0, v[148:149]
	s_mov_b32 m0, s8
	s_nop 0
	global_load_lds_dwordx4 v[130:131], off
	v_lshl_add_u64 v[130:131], s[6:7], 0, v[152:153]
	s_add_i32 m0, s8, 0x2000
	s_nop 0
	global_load_lds_dwordx4 v[130:131], off
	s_waitcnt vmcnt(6)
	s_barrier
	s_setprio 1
	v_mfma_f32_16x16x32_bf16 v[50:53], v[214:217], v[180:183], v[50:53]
	v_mfma_f32_16x16x32_bf16 v[42:45], v[222:225], v[180:183], v[42:45]
	v_mfma_f32_16x16x32_bf16 v[34:37], v[214:217], v[190:193], v[34:37]
	v_mfma_f32_16x16x32_bf16 v[26:29], v[222:225], v[190:193], v[26:29]
	v_mfma_f32_16x16x32_bf16 v[18:21], v[214:217], v[198:201], v[18:21]
	v_mfma_f32_16x16x32_bf16 v[10:13], v[222:225], v[198:201], v[10:13]
	v_mfma_f32_16x16x32_bf16 v[6:9], v[214:217], v[206:209], v[6:9]
	v_mfma_f32_16x16x32_bf16 v[2:5], v[222:225], v[206:209], v[2:5]
	v_mfma_f32_16x16x32_bf16 v[50:53], v[218:221], v[184:187], v[50:53]
	v_mfma_f32_16x16x32_bf16 v[42:45], v[226:229], v[184:187], v[42:45]
	v_mfma_f32_16x16x32_bf16 v[34:37], v[218:221], v[194:197], v[34:37]
	v_mfma_f32_16x16x32_bf16 v[26:29], v[226:229], v[194:197], v[26:29]
	v_mfma_f32_16x16x32_bf16 v[18:21], v[218:221], v[202:205], v[18:21]
	v_mfma_f32_16x16x32_bf16 v[10:13], v[226:229], v[202:205], v[10:13]
	v_mfma_f32_16x16x32_bf16 v[6:9], v[218:221], v[210:213], v[6:9]
	v_mfma_f32_16x16x32_bf16 v[2:5], v[226:229], v[210:213], v[2:5]
	s_setprio 0
	s_add_i32 s73, s73, 2
	s_add_u32 s2, s2, 0x100
	s_addc_u32 s3, s3, 0
	s_add_u32 s71, s71, 0x100
	s_addc_u32 s72, s72, 0
	s_cmp_gt_u32 s73, 13
	s_barrier
	s_cbranch_scc1 .Lpeel_p1_exit

.Lpeel_p1_exit:
	v_mov_b32_e32 v154, v167
	v_mov_b32_e32 v194, v169
	s_cmp_lt_i32 s70, 16
	v_add_u32_e32 v182, s55, v154
	v_lshl_add_u32 v180, s0, 8, v182
	v_ashrrev_i32_e32 v181, 31, v180
	v_lshl_add_u64 v[130:131], v[180:181], 2, s[62:63]
	global_load_dword v178, v[130:131], off
	global_load_dword v176, v[130:131], off offset:64
	global_load_dword v174, v[130:131], off offset:128
	global_load_dword v172, v[130:131], off offset:192
	global_load_dword v170, v[130:131], off offset:512
	global_load_dword v168, v[130:131], off offset:576
	global_load_dword v166, v[130:131], off offset:640
	global_load_dword v164, v[130:131], off offset:704
	s_mov_b64 s[2:3], -1
	s_cbranch_scc0 .LBB0_226
	v_lshl_add_u32 v183, v194, 2, s58
	v_lshl_add_u32 v186, s70, 6, v183
	v_ashrrev_i32_e32 v187, 31, v186
	v_readlane_b32 s8, v248, 18
	v_lshlrev_b64 v[184:185], 2, v[186:187]
	v_readlane_b32 s20, v248, 30
	v_readlane_b32 s21, v248, 31
	v_lshl_add_u64 v[134:135], s[34:35], 0, v[184:185]
	s_cmp_lg_u32 s0, 64
	v_lshl_add_u64 v[130:131], s[20:21], 0, v[184:185]
	global_load_dwordx4 v[130:133], v[130:131], off
	s_nop 0
	global_load_dwordx4 v[138:141], v[134:135], off
	v_lshl_add_u64 v[134:135], s[36:37], 0, v[184:185]
	global_load_dwordx4 v[134:137], v[134:135], off
	v_readlane_b32 s9, v248, 19
	v_readlane_b32 s10, v248, 20
	v_readlane_b32 s11, v248, 21
	v_readlane_b32 s12, v248, 22
	v_readlane_b32 s13, v248, 23
	v_readlane_b32 s14, v248, 24
	v_readlane_b32 s15, v248, 25
	v_readlane_b32 s16, v248, 26
	v_readlane_b32 s17, v248, 27
	v_readlane_b32 s18, v248, 28
	v_readlane_b32 s19, v248, 29
	v_readlane_b32 s22, v248, 32
	v_readlane_b32 s23, v248, 33
	s_cbranch_scc0 .LBB0_223
	v_cmp_lt_i32_e32 vcc, 13, v154
	v_lshlrev_b32_e32 v192, 2, v183
	s_waitcnt vmcnt(0)
	v_mul_f32_e32 v188, v164, v164
	v_pk_mul_f32 v[190:191], v[14:15], v[6:7]
	s_and_saveexec_b64 s[2:3], vcc
	s_cbranch_execz .LBB0_218
	v_pk_mul_f32 v[144:145], v[80:81], v[72:73]
	v_pk_mul_f32 v[142:143], v[78:79], v[70:71]
	v_mul_f32_e32 v196, v172, v172
	v_add_lshl_u32 v193, s59, v154, 8
	s_add_i32 s1, 0, 0x20010
	v_pk_mul_f32 v[142:143], v[142:143], v[196:197] op_sel_hi:[1,0]
	v_pk_mul_f32 v[144:145], v[144:145], v[196:197] op_sel_hi:[1,0]
	v_add3_u32 v195, s1, v193, v192
	v_readlane_b32 s6, v248, 43
	ds_write_b128 v195, v[142:145]
	v_pk_mul_f32 v[144:145], v[16:17], v[8:9]
	v_readlane_b32 s7, v248, 44
	v_pk_mul_f32 v[142:143], v[190:191], v[188:189] op_sel_hi:[1,0]
	v_pk_mul_f32 v[144:145], v[144:145], v[188:189] op_sel_hi:[1,0]
	v_add3_u32 v193, s68, v193, v192
	s_andn2_b64 vcc, exec, s[6:7]
	ds_write_b128 v193, v[142:145]
	s_cbranch_vccnz .LBB0_218
	s_lshl_b32 s1, s0, 1
	v_add3_u32 v196, s1, -14, v154
	v_ashrrev_i32_e32 v197, 31, v196
	v_readlane_b32 s6, v248, 47
	v_lshlrev_b64 v[196:197], 12, v[196:197]
	v_readlane_b32 s7, v248, 48
	s_nop 1
	v_lshl_add_u64 v[196:197], s[6:7], 0, v[196:197]
	v_lshl_add_u64 v[196:197], v[186:187], 2, v[196:197]
	global_store_dwordx4 v[196:197], v[142:145], off

.LBB0_1089:
	s_ashr_i32 s39, s38, 31
	v_cmp_lt_i64_e32 vcc, s[40:41], v[196:197]
	s_lshl_b64 s[40:41], s[38:39], 19
	s_add_u32 s40, s47, s40
	s_addc_u32 s41, s48, s41
	s_and_b64 s[42:43], vcc, exec
	s_cselect_b32 s33, s41, s1
	s_cselect_b32 s39, s40, s0
	s_ashr_i32 s37, s36, 31
	s_lshl_b64 s[42:43], s[36:37], 19
	s_add_u32 s42, s49, s42
	s_addc_u32 s43, s50, s43
	s_and_b64 s[44:45], vcc, exec
	s_cselect_b32 s37, s43, s3
	s_cselect_b32 s71, s42, s2
	s_add_u32 s0, s0, 0x40080
	s_addc_u32 s1, s1, 0
	s_add_u32 s72, s2, 0x100
	s_addc_u32 s73, s3, 0
	s_mov_b32 s74, -2
.Lpeel_p8:
	ds_read_b128 v[130:133], v181
	ds_read_b128 v[134:137], v181 offset:1024
	ds_read_b128 v[138:141], v181 offset:2048
	ds_read_b128 v[142:145], v181 offset:3072
	s_add_u32 s2, s0, 0xfffc0080
	s_addc_u32 s3, s1, -1
	s_cmp_eq_u32 s74, 12
	s_cselect_b32 s45, s33, s3
	s_cselect_b32 s44, s39, s2
	s_cselect_b32 s3, s37, s73
	s_cselect_b32 s2, s71, s72
	v_lshl_add_u64 v[200:201], s[0:1], 0, v[192:193]
	s_add_i32 m0, s52, 0xc000
	ds_read_b128 v[146:149], v183
	ds_read_b128 v[150:153], v183 offset:1024
	ds_read_b128 v[154:157], v183 offset:2048
	ds_read_b128 v[158:161], v183 offset:3072
	ds_read_b128 v[162:165], v183 offset:4096
	ds_read_b128 v[166:169], v183 offset:5120
	ds_read_b128 v[170:173], v183 offset:6144
	ds_read_b128 v[174:177], v183 offset:7168
	global_load_lds_dwordx4 v[200:201], off
	v_lshl_add_u64 v[200:201], s[0:1], 0, v[194:195]
	s_add_i32 m0, s52, 0xe000
	s_nop 0
	global_load_lds_dwordx4 v[200:201], off
	s_waitcnt lgkmcnt(8)
	s_barrier
	s_waitcnt lgkmcnt(0)
	s_setprio 1
	s_waitcnt lgkmcnt(0)
	v_mfma_f32_16x16x32_bf16 v[62:65], v[130:133], v[146:149], 0
	v_mfma_f32_16x16x32_bf16 v[30:33], v[138:141], v[146:149], 0
	v_mfma_f32_16x16x32_bf16 v[54:57], v[130:133], v[154:157], 0
	v_mfma_f32_16x16x32_bf16 v[22:25], v[138:141], v[154:157], 0
	v_mfma_f32_16x16x32_bf16 v[46:49], v[130:133], v[162:165], 0
	v_mfma_f32_16x16x32_bf16 v[14:17], v[138:141], v[162:165], 0
	v_mfma_f32_16x16x32_bf16 v[38:41], v[130:133], v[170:173], 0
	v_mfma_f32_16x16x32_bf16 v[6:9], v[138:141], v[170:173], 0
	v_mfma_f32_16x16x32_bf16 v[62:65], v[134:137], v[150:153], v[62:65]
	v_mfma_f32_16x16x32_bf16 v[30:33], v[142:145], v[150:153], v[30:33]
	v_mfma_f32_16x16x32_bf16 v[54:57], v[134:137], v[158:161], v[54:57]
	v_mfma_f32_16x16x32_bf16 v[22:25], v[142:145], v[158:161], v[22:25]
	v_mfma_f32_16x16x32_bf16 v[46:49], v[134:137], v[166:169], v[46:49]
	v_mfma_f32_16x16x32_bf16 v[14:17], v[142:145], v[166:169], v[14:17]
	v_mfma_f32_16x16x32_bf16 v[38:41], v[134:137], v[174:177], v[38:41]
	v_mfma_f32_16x16x32_bf16 v[6:9], v[142:145], v[174:177], v[6:9]
	s_setprio 0
	s_barrier
	s_add_i32 s75, s66, s51
	v_lshl_add_u64 v[208:209], s[2:3], 0, v[186:187]
	s_mov_b32 m0, s75
	ds_read_b128 v[200:203], v206
	ds_read_b128 v[212:215], v206 offset:1024
	ds_read_b128 v[216:219], v206 offset:2048
	ds_read_b128 v[220:223], v206 offset:3072
	global_load_lds_dwordx4 v[208:209], off
	v_lshl_add_u64 v[224:225], s[2:3], 0, v[190:191]
	s_add_i32 m0, s75, 0x2000
	s_nop 0
	global_load_lds_dwordx4 v[224:225], off
	s_barrier
	s_waitcnt lgkmcnt(0)
	s_setprio 1
	s_waitcnt lgkmcnt(0)
	v_mfma_f32_16x16x32_bf16 v[58:61], v[200:203], v[146:149], 0
	v_mfma_f32_16x16x32_bf16 v[26:29], v[216:219], v[146:149], 0
	v_mfma_f32_16x16x32_bf16 v[50:53], v[200:203], v[154:157], 0
	v_mfma_f32_16x16x32_bf16 v[18:21], v[216:219], v[154:157], 0
	v_mfma_f32_16x16x32_bf16 v[42:45], v[200:203], v[162:165], 0
	v_mfma_f32_16x16x32_bf16 v[10:13], v[216:219], v[162:165], 0
	v_mfma_f32_16x16x32_bf16 v[34:37], v[200:203], v[170:173], 0
	v_mfma_f32_16x16x32_bf16 v[2:5], v[216:219], v[170:173], 0
	v_mfma_f32_16x16x32_bf16 v[58:61], v[212:215], v[150:153], v[58:61]
	v_mfma_f32_16x16x32_bf16 v[26:29], v[220:223], v[150:153], v[26:29]
	v_mfma_f32_16x16x32_bf16 v[50:53], v[212:215], v[158:161], v[50:53]
	v_mfma_f32_16x16x32_bf16 v[18:21], v[220:223], v[158:161], v[18:21]
	v_mfma_f32_16x16x32_bf16 v[42:45], v[212:215], v[166:169], v[42:45]
	v_mfma_f32_16x16x32_bf16 v[10:13], v[220:223], v[166:169], v[10:13]
	v_mfma_f32_16x16x32_bf16 v[34:37], v[212:215], v[174:177], v[34:37]
	v_mfma_f32_16x16x32_bf16 v[2:5], v[220:223], v[174:177], v[2:5]
	s_setprio 0
	s_mov_b32 m0, s52
	v_lshl_add_u64 v[226:227], s[44:45], 0, v[184:185]
	s_barrier
	ds_read_b128 v[146:149], v183 offset:16384
	ds_read_b128 v[150:153], v183 offset:17408
	ds_read_b128 v[154:157], v183 offset:18432
	ds_read_b128 v[158:161], v183 offset:19456
	ds_read_b128 v[162:165], v183 offset:20480
	ds_read_b128 v[166:169], v183 offset:21504
	ds_read_b128 v[170:173], v183 offset:22528
	ds_read_b128 v[174:177], v183 offset:23552
	global_load_lds_dwordx4 v[226:227], off
	v_lshl_add_u64 v[228:229], s[44:45], 0, v[188:189]
	s_mov_b32 m0, s53
	s_nop 0
	global_load_lds_dwordx4 v[228:229], off
	s_barrier
	s_waitcnt lgkmcnt(0)
	s_setprio 1
	s_waitcnt lgkmcnt(0)
	v_mfma_f32_16x16x32_bf16 v[126:129], v[130:133], v[146:149], 0
	v_mfma_f32_16x16x32_bf16 v[102:105], v[138:141], v[146:149], 0
	v_mfma_f32_16x16x32_bf16 v[122:125], v[130:133], v[154:157], 0
	v_mfma_f32_16x16x32_bf16 v[90:93], v[138:141], v[154:157], 0
	v_mfma_f32_16x16x32_bf16 v[118:121], v[130:133], v[162:165], 0
	v_mfma_f32_16x16x32_bf16 v[78:81], v[138:141], v[162:165], 0
	v_mfma_f32_16x16x32_bf16 v[106:109], v[130:133], v[170:173], 0
	v_mfma_f32_16x16x32_bf16 v[70:73], v[138:141], v[170:173], 0
	v_mfma_f32_16x16x32_bf16 v[126:129], v[134:137], v[150:153], v[126:129]
	v_mfma_f32_16x16x32_bf16 v[102:105], v[142:145], v[150:153], v[102:105]
	v_mfma_f32_16x16x32_bf16 v[122:125], v[134:137], v[158:161], v[122:125]
	v_mfma_f32_16x16x32_bf16 v[90:93], v[142:145], v[158:161], v[90:93]
	v_mfma_f32_16x16x32_bf16 v[118:121], v[134:137], v[166:169], v[118:121]
	v_mfma_f32_16x16x32_bf16 v[78:81], v[142:145], v[166:169], v[78:81]
	v_mfma_f32_16x16x32_bf16 v[106:109], v[134:137], v[174:177], v[106:109]
	v_mfma_f32_16x16x32_bf16 v[70:73], v[142:145], v[174:177], v[70:73]
	s_setprio 0
	s_barrier
	s_add_u32 s76, s2, 0x40000
	s_addc_u32 s77, s3, 0
	s_add_i32 s75, s67, s51
	v_lshl_add_u64 v[130:131], s[76:77], 0, v[186:187]
	s_mov_b32 m0, s75
	s_nop 0
	global_load_lds_dwordx4 v[130:131], off
	v_lshl_add_u64 v[130:131], s[76:77], 0, v[190:191]
	s_add_i32 m0, s75, 0x2000
	s_nop 0
	global_load_lds_dwordx4 v[130:131], off
	s_waitcnt vmcnt(6)
	s_barrier
	s_setprio 1
	v_mfma_f32_16x16x32_bf16 v[114:117], v[200:203], v[146:149], 0
	v_mfma_f32_16x16x32_bf16 v[86:89], v[216:219], v[146:149], 0
	v_mfma_f32_16x16x32_bf16 v[110:113], v[200:203], v[154:157], 0
	v_mfma_f32_16x16x32_bf16 v[82:85], v[216:219], v[154:157], 0
	v_mfma_f32_16x16x32_bf16 v[98:101], v[200:203], v[162:165], 0
	v_mfma_f32_16x16x32_bf16 v[74:77], v[216:219], v[162:165], 0
	v_mfma_f32_16x16x32_bf16 v[94:97], v[200:203], v[170:173], 0
	v_mfma_f32_16x16x32_bf16 v[66:69], v[216:219], v[170:173], 0
	v_mfma_f32_16x16x32_bf16 v[114:117], v[212:215], v[150:153], v[114:117]
	v_mfma_f32_16x16x32_bf16 v[86:89], v[220:223], v[150:153], v[86:89]
	v_mfma_f32_16x16x32_bf16 v[110:113], v[212:215], v[158:161], v[110:113]
	v_mfma_f32_16x16x32_bf16 v[82:85], v[220:223], v[158:161], v[82:85]
	v_mfma_f32_16x16x32_bf16 v[98:101], v[212:215], v[166:169], v[98:101]
	v_mfma_f32_16x16x32_bf16 v[74:77], v[220:223], v[166:169], v[74:77]
	v_mfma_f32_16x16x32_bf16 v[94:97], v[212:215], v[174:177], v[94:97]
	v_mfma_f32_16x16x32_bf16 v[66:69], v[220:223], v[174:177], v[66:69]
	s_setprio 0
	s_add_i32 s75, 0, 0x18000
	v_add_u32_e32 v142, s75, v1
	s_barrier
	ds_read_b128 v[130:133], v142
	ds_read_b128 v[134:137], v142 offset:1024
	ds_read_b128 v[138:141], v142 offset:2048
	ds_read_b128 v[142:145], v142 offset:3072
	s_add_u32 s44, s44, 0x40000
	s_addc_u32 s45, s45, 0
	s_mov_b32 m0, s54
	v_lshl_add_u64 v[200:201], s[44:45], 0, v[184:185]
	ds_read_b128 v[146:149], v183 offset:32768
	ds_read_b128 v[150:153], v183 offset:33792
	ds_read_b128 v[154:157], v183 offset:34816
	ds_read_b128 v[158:161], v183 offset:35840
	ds_read_b128 v[162:165], v183 offset:36864
	ds_read_b128 v[166:169], v183 offset:37888
	ds_read_b128 v[170:173], v183 offset:38912
	ds_read_b128 v[174:177], v183 offset:39936
	global_load_lds_dwordx4 v[200:201], off
	v_lshl_add_u64 v[200:201], s[44:45], 0, v[188:189]
	s_mov_b32 m0, s55
	s_nop 0
	global_load_lds_dwordx4 v[200:201], off
	s_waitcnt lgkmcnt(8)
	s_barrier
	s_waitcnt lgkmcnt(0)
	s_setprio 1
	s_waitcnt lgkmcnt(0)
	v_mfma_f32_16x16x32_bf16 v[62:65], v[130:133], v[146:149], v[62:65]
	v_mfma_f32_16x16x32_bf16 v[30:33], v[138:141], v[146:149], v[30:33]
	v_mfma_f32_16x16x32_bf16 v[54:57], v[130:133], v[154:157], v[54:57]
	v_mfma_f32_16x16x32_bf16 v[22:25], v[138:141], v[154:157], v[22:25]
	v_mfma_f32_16x16x32_bf16 v[46:49], v[130:133], v[162:165], v[46:49]
	v_mfma_f32_16x16x32_bf16 v[14:17], v[138:141], v[162:165], v[14:17]
	v_mfma_f32_16x16x32_bf16 v[38:41], v[130:133], v[170:173], v[38:41]
	v_mfma_f32_16x16x32_bf16 v[6:9], v[138:141], v[170:173], v[6:9]
	v_mfma_f32_16x16x32_bf16 v[62:65], v[134:137], v[150:153], v[62:65]
	v_mfma_f32_16x16x32_bf16 v[30:33], v[142:145], v[150:153], v[30:33]
	v_mfma_f32_16x16x32_bf16 v[54:57], v[134:137], v[158:161], v[54:57]
	v_mfma_f32_16x16x32_bf16 v[22:25], v[142:145], v[158:161], v[22:25]
	v_mfma_f32_16x16x32_bf16 v[46:49], v[134:137], v[166:169], v[46:49]
	v_mfma_f32_16x16x32_bf16 v[14:17], v[142:145], v[166:169], v[14:17]
	v_mfma_f32_16x16x32_bf16 v[38:41], v[134:137], v[174:177], v[38:41]
	v_mfma_f32_16x16x32_bf16 v[6:9], v[142:145], v[174:177], v[6:9]
	s_setprio 0
	s_barrier
	s_add_i32 s44, 0, 0x1c000
	s_add_i32 s45, s75, s51
	v_add_u32_e32 v207, s44, v1
	v_lshl_add_u64 v[208:209], v[208:209], 0, s[22:23]
	s_mov_b32 m0, s45
	ds_read_b128 v[200:203], v207
	ds_read_b128 v[212:215], v207 offset:1024
	ds_read_b128 v[216:219], v207 offset:2048
	ds_read_b128 v[220:223], v207 offset:3072
	global_load_lds_dwordx4 v[208:209], off
	v_lshl_add_u64 v[208:209], v[224:225], 0, s[22:23]
	s_add_i32 m0, s45, 0x2000
	s_nop 0
	global_load_lds_dwordx4 v[208:209], off
	s_barrier
	s_waitcnt lgkmcnt(0)
	s_setprio 1
	s_waitcnt lgkmcnt(0)
	v_mfma_f32_16x16x32_bf16 v[58:61], v[200:203], v[146:149], v[58:61]
	v_mfma_f32_16x16x32_bf16 v[26:29], v[216:219], v[146:149], v[26:29]
	v_mfma_f32_16x16x32_bf16 v[50:53], v[200:203], v[154:157], v[50:53]
	v_mfma_f32_16x16x32_bf16 v[18:21], v[216:219], v[154:157], v[18:21]
	v_mfma_f32_16x16x32_bf16 v[42:45], v[200:203], v[162:165], v[42:45]
	v_mfma_f32_16x16x32_bf16 v[10:13], v[216:219], v[162:165], v[10:13]
	v_mfma_f32_16x16x32_bf16 v[34:37], v[200:203], v[170:173], v[34:37]
	v_mfma_f32_16x16x32_bf16 v[2:5], v[216:219], v[170:173], v[2:5]
	v_mfma_f32_16x16x32_bf16 v[58:61], v[212:215], v[150:153], v[58:61]
	v_mfma_f32_16x16x32_bf16 v[26:29], v[220:223], v[150:153], v[26:29]
	v_mfma_f32_16x16x32_bf16 v[50:53], v[212:215], v[158:161], v[50:53]
	v_mfma_f32_16x16x32_bf16 v[18:21], v[220:223], v[158:161], v[18:21]
	v_mfma_f32_16x16x32_bf16 v[42:45], v[212:215], v[166:169], v[42:45]
	v_mfma_f32_16x16x32_bf16 v[10:13], v[220:223], v[166:169], v[10:13]
	v_mfma_f32_16x16x32_bf16 v[34:37], v[212:215], v[174:177], v[34:37]
	v_mfma_f32_16x16x32_bf16 v[2:5], v[220:223], v[174:177], v[2:5]
	s_setprio 0
	s_mov_b32 m0, s59
	v_lshl_add_u64 v[208:209], v[226:227], 0, s[22:23]
	s_barrier
	ds_read_b128 v[146:149], v183 offset:49152
	ds_read_b128 v[150:153], v183 offset:50176
	ds_read_b128 v[154:157], v183 offset:51200
	ds_read_b128 v[158:161], v183 offset:52224
	ds_read_b128 v[162:165], v183 offset:53248
	ds_read_b128 v[166:169], v183 offset:54272
	ds_read_b128 v[170:173], v183 offset:55296
	ds_read_b128 v[174:177], v183 offset:56320
	global_load_lds_dwordx4 v[208:209], off
	v_lshl_add_u64 v[208:209], v[228:229], 0, s[22:23]
	s_mov_b32 m0, s60
	s_nop 0
	global_load_lds_dwordx4 v[208:209], off
	s_barrier
	s_waitcnt lgkmcnt(0)
	s_setprio 1
	s_waitcnt lgkmcnt(0)
	v_mfma_f32_16x16x32_bf16 v[126:129], v[130:133], v[146:149], v[126:129]
	v_mfma_f32_16x16x32_bf16 v[102:105], v[138:141], v[146:149], v[102:105]
	v_mfma_f32_16x16x32_bf16 v[122:125], v[130:133], v[154:157], v[122:125]
	v_mfma_f32_16x16x32_bf16 v[90:93], v[138:141], v[154:157], v[90:93]
	v_mfma_f32_16x16x32_bf16 v[118:121], v[130:133], v[162:165], v[118:121]
	v_mfma_f32_16x16x32_bf16 v[78:81], v[138:141], v[162:165], v[78:81]
	v_mfma_f32_16x16x32_bf16 v[106:109], v[130:133], v[170:173], v[106:109]
	v_mfma_f32_16x16x32_bf16 v[70:73], v[138:141], v[170:173], v[70:73]
	v_mfma_f32_16x16x32_bf16 v[126:129], v[134:137], v[150:153], v[126:129]
	v_mfma_f32_16x16x32_bf16 v[102:105], v[142:145], v[150:153], v[102:105]
	v_mfma_f32_16x16x32_bf16 v[122:125], v[134:137], v[158:161], v[122:125]
	v_mfma_f32_16x16x32_bf16 v[90:93], v[142:145], v[158:161], v[90:93]
	v_mfma_f32_16x16x32_bf16 v[118:121], v[134:137], v[166:169], v[118:121]
	v_mfma_f32_16x16x32_bf16 v[78:81], v[142:145], v[166:169], v[78:81]
	v_mfma_f32_16x16x32_bf16 v[106:109], v[134:137], v[174:177], v[106:109]
	v_mfma_f32_16x16x32_bf16 v[70:73], v[142:145], v[174:177], v[70:73]
	s_setprio 0
	s_barrier
	s_add_u32 s2, s2, 0x40080
	s_addc_u32 s3, s3, 0
	s_add_i32 s44, s44, s51
	v_lshl_add_u64 v[130:131], s[2:3], 0, v[186:187]
	s_mov_b32 m0, s44
	s_nop 0
	global_load_lds_dwordx4 v[130:131], off
	v_lshl_add_u64 v[130:131], s[2:3], 0, v[190:191]
	s_add_i32 m0, s44, 0x2000
	s_nop 0
	global_load_lds_dwordx4 v[130:131], off
	s_waitcnt vmcnt(6)
	s_barrier
	s_setprio 1
	v_mfma_f32_16x16x32_bf16 v[114:117], v[200:203], v[146:149], v[114:117]
	v_mfma_f32_16x16x32_bf16 v[86:89], v[216:219], v[146:149], v[86:89]
	v_mfma_f32_16x16x32_bf16 v[110:113], v[200:203], v[154:157], v[110:113]
	v_mfma_f32_16x16x32_bf16 v[82:85], v[216:219], v[154:157], v[82:85]
	v_mfma_f32_16x16x32_bf16 v[98:101], v[200:203], v[162:165], v[98:101]
	v_mfma_f32_16x16x32_bf16 v[74:77], v[216:219], v[162:165], v[74:77]
	v_mfma_f32_16x16x32_bf16 v[94:97], v[200:203], v[170:173], v[94:97]
	v_mfma_f32_16x16x32_bf16 v[66:69], v[216:219], v[170:173], v[66:69]
	v_mfma_f32_16x16x32_bf16 v[114:117], v[212:215], v[150:153], v[114:117]
	v_mfma_f32_16x16x32_bf16 v[86:89], v[220:223], v[150:153], v[86:89]
	v_mfma_f32_16x16x32_bf16 v[110:113], v[212:215], v[158:161], v[110:113]
	v_mfma_f32_16x16x32_bf16 v[82:85], v[220:223], v[158:161], v[82:85]
	v_mfma_f32_16x16x32_bf16 v[98:101], v[212:215], v[166:169], v[98:101]
	v_mfma_f32_16x16x32_bf16 v[74:77], v[220:223], v[166:169], v[74:77]
	v_mfma_f32_16x16x32_bf16 v[94:97], v[212:215], v[174:177], v[94:97]
	v_mfma_f32_16x16x32_bf16 v[66:69], v[220:223], v[174:177], v[66:69]
	s_setprio 0
	s_add_i32 s74, s74, 2
	s_add_u32 s0, s0, 0x100
	s_addc_u32 s1, s1, 0
	s_add_u32 s72, s72, 0x100
	s_addc_u32 s73, s73, 0
	s_cmp_gt_u32 s74, 13
	s_barrier
	s_cbranch_scc1 .Lpeel_p8_exit

.Lpeel_p8_exit:
	v_mov_b32_e32 v130, v211
	v_mov_b32_e32 v207, v178
	s_cmp_lg_u32 s6, 64
	v_lshl_add_u32 v163, v130, 3, s58
	v_lshl_add_u32 v200, s7, 7, v163
	s_mov_b64 s[0:1], -1
	s_cbranch_scc0 .LBB0_1104
	v_cmp_lt_i32_e32 vcc, 13, v207
	v_lshlrev_b32_e32 v164, 2, v163
	s_and_saveexec_b64 s[0:1], vcc
	s_cbranch_execz .LBB0_1095
	v_add_lshl_u32 v130, s61, v207, 9
	s_add_i32 s2, 0, 0x20010
	v_add3_u32 v131, s2, v130, v164
	v_readlane_b32 s2, v248, 51
	v_readlane_b32 s3, v248, 52
	v_add3_u32 v130, s68, v130, v164
	s_andn2_b64 vcc, exec, s[2:3]
	ds_write_b128 v131, v[38:41]
	ds_write_b128 v131, v[6:9] offset:16
	ds_write_b128 v130, v[106:109]
	ds_write_b128 v131, v[70:73] offset:2064
	s_cbranch_vccnz .LBB0_1095
	s_lshl_b32 s2, s6, 1
	v_add3_u32 v132, s2, -14, v207
	v_readlane_b32 s2, v248, 43
	v_readlane_b32 s3, v248, 44
	v_ashrrev_i32_e32 v201, 31, v200
	s_nop 0
	v_mov_b64_e32 v[130:131], s[2:3]
	v_mad_i64_i32 v[130:131], s[2:3], v132, s69, v[130:131]
	v_lshl_add_u64 v[130:131], v[200:201], 2, v[130:131]
	global_store_dwordx4 v[130:131], v[106:109], off
	global_store_dwordx4 v[130:131], v[70:73], off offset:16

.LBB0_1196:
	s_add_u32 s16, s16, 0xb0080
	s_addc_u32 s17, s17, 0
	s_add_u32 s52, s18, 0x100
	s_addc_u32 s53, s19, 0
	s_mov_b32 s54, -2
.Lpeel_p10:
	ds_read_b128 v[152:155], v149
	ds_read_b128 v[156:159], v149 offset:1024
	ds_read_b128 v[160:163], v149 offset:2048
	ds_read_b128 v[164:167], v149 offset:3072
	s_add_u32 s18, s16, 0xfff50080
	s_addc_u32 s19, s17, -1
	s_cmp_eq_u32 s54, 40
	s_cselect_b32 s21, s3, s19
	s_cselect_b32 s20, s2, s18
	s_cselect_b32 s19, s5, s53
	s_cselect_b32 s18, s4, s52
	v_lshl_add_u64 v[146:147], s[16:17], 0, v[138:139]
	s_add_i32 m0, s30, 0xc000
	ds_read_b128 v[168:171], v150
	ds_read_b128 v[172:175], v150 offset:1024
	ds_read_b128 v[180:183], v150 offset:2048
	ds_read_b128 v[184:187], v150 offset:3072
	ds_read_b128 v[188:191], v150 offset:4096
	ds_read_b128 v[192:195], v150 offset:5120
	ds_read_b128 v[196:199], v150 offset:6144
	ds_read_b128 v[200:203], v150 offset:7168
	global_load_lds_dwordx4 v[146:147], off
	v_lshl_add_u64 v[146:147], s[16:17], 0, v[140:141]
	s_add_i32 m0, s30, 0xe000
	s_nop 0
	global_load_lds_dwordx4 v[146:147], off
	s_waitcnt lgkmcnt(8)
	s_barrier
	s_waitcnt lgkmcnt(0)
	s_setprio 1
	s_waitcnt lgkmcnt(0)
	v_mfma_f32_16x16x32_bf16 v[126:129], v[152:155], v[168:171], 0
	v_mfma_f32_16x16x32_bf16 v[122:125], v[160:163], v[168:171], 0
	v_mfma_f32_16x16x32_bf16 v[114:117], v[152:155], v[180:183], 0
	v_mfma_f32_16x16x32_bf16 v[106:109], v[160:163], v[180:183], 0
	v_mfma_f32_16x16x32_bf16 v[98:101], v[152:155], v[188:191], 0
	v_mfma_f32_16x16x32_bf16 v[90:93], v[160:163], v[188:191], 0
	v_mfma_f32_16x16x32_bf16 v[82:85], v[152:155], v[196:199], 0
	v_mfma_f32_16x16x32_bf16 v[74:77], v[160:163], v[196:199], 0
	v_mfma_f32_16x16x32_bf16 v[126:129], v[156:159], v[172:175], v[126:129]
	v_mfma_f32_16x16x32_bf16 v[122:125], v[164:167], v[172:175], v[122:125]
	v_mfma_f32_16x16x32_bf16 v[114:117], v[156:159], v[184:187], v[114:117]
	v_mfma_f32_16x16x32_bf16 v[106:109], v[164:167], v[184:187], v[106:109]
	v_mfma_f32_16x16x32_bf16 v[98:101], v[156:159], v[192:195], v[98:101]
	v_mfma_f32_16x16x32_bf16 v[90:93], v[164:167], v[192:195], v[90:93]
	v_mfma_f32_16x16x32_bf16 v[82:85], v[156:159], v[200:203], v[82:85]
	v_mfma_f32_16x16x32_bf16 v[74:77], v[164:167], v[200:203], v[74:77]
	s_setprio 0
	s_barrier
	s_add_i32 s55, s41, s27
	v_lshl_add_u64 v[146:147], s[18:19], 0, v[134:135]
	s_mov_b32 m0, s55
	ds_read_b128 v[206:209], v151
	ds_read_b128 v[212:215], v151 offset:1024
	ds_read_b128 v[216:219], v151 offset:2048
	ds_read_b128 v[220:223], v151 offset:3072
	global_load_lds_dwordx4 v[146:147], off
	v_lshl_add_u64 v[176:177], s[18:19], 0, v[136:137]
	s_add_i32 m0, s55, 0x2000
	s_nop 0
	global_load_lds_dwordx4 v[176:177], off
	s_barrier
	s_waitcnt lgkmcnt(0)
	s_setprio 1
	s_waitcnt lgkmcnt(0)
	v_mfma_f32_16x16x32_bf16 v[118:121], v[206:209], v[168:171], 0
	v_mfma_f32_16x16x32_bf16 v[110:113], v[216:219], v[168:171], 0
	v_mfma_f32_16x16x32_bf16 v[102:105], v[206:209], v[180:183], 0
	v_mfma_f32_16x16x32_bf16 v[94:97], v[216:219], v[180:183], 0
	v_mfma_f32_16x16x32_bf16 v[86:89], v[206:209], v[188:191], 0
	v_mfma_f32_16x16x32_bf16 v[78:81], v[216:219], v[188:191], 0
	v_mfma_f32_16x16x32_bf16 v[70:73], v[206:209], v[196:199], 0
	v_mfma_f32_16x16x32_bf16 v[66:69], v[216:219], v[196:199], 0
	v_mfma_f32_16x16x32_bf16 v[118:121], v[212:215], v[172:175], v[118:121]
	v_mfma_f32_16x16x32_bf16 v[110:113], v[220:223], v[172:175], v[110:113]
	v_mfma_f32_16x16x32_bf16 v[102:105], v[212:215], v[184:187], v[102:105]
	v_mfma_f32_16x16x32_bf16 v[94:97], v[220:223], v[184:187], v[94:97]
	v_mfma_f32_16x16x32_bf16 v[86:89], v[212:215], v[192:195], v[86:89]
	v_mfma_f32_16x16x32_bf16 v[78:81], v[220:223], v[192:195], v[78:81]
	v_mfma_f32_16x16x32_bf16 v[70:73], v[212:215], v[200:203], v[70:73]
	v_mfma_f32_16x16x32_bf16 v[66:69], v[220:223], v[200:203], v[66:69]
	s_setprio 0
	s_mov_b32 m0, s30
	v_lshl_add_u64 v[224:225], s[20:21], 0, v[130:131]
	s_barrier
	ds_read_b128 v[168:171], v150 offset:16384
	ds_read_b128 v[172:175], v150 offset:17408
	ds_read_b128 v[180:183], v150 offset:18432
	ds_read_b128 v[184:187], v150 offset:19456
	ds_read_b128 v[188:191], v150 offset:20480
	ds_read_b128 v[192:195], v150 offset:21504
	ds_read_b128 v[196:199], v150 offset:22528
	ds_read_b128 v[200:203], v150 offset:23552
	global_load_lds_dwordx4 v[224:225], off
	v_lshl_add_u64 v[226:227], s[20:21], 0, v[132:133]
	s_mov_b32 m0, s31
	s_nop 0
	global_load_lds_dwordx4 v[226:227], off
	s_barrier
	s_waitcnt lgkmcnt(0)
	s_setprio 1
	s_waitcnt lgkmcnt(0)
	v_mfma_f32_16x16x32_bf16 v[62:65], v[152:155], v[168:171], 0
	v_mfma_f32_16x16x32_bf16 v[58:61], v[160:163], v[168:171], 0
	v_mfma_f32_16x16x32_bf16 v[50:53], v[152:155], v[180:183], 0
	v_mfma_f32_16x16x32_bf16 v[42:45], v[160:163], v[180:183], 0
	v_mfma_f32_16x16x32_bf16 v[34:37], v[152:155], v[188:191], 0
	v_mfma_f32_16x16x32_bf16 v[26:29], v[160:163], v[188:191], 0
	v_mfma_f32_16x16x32_bf16 v[18:21], v[152:155], v[196:199], 0
	v_mfma_f32_16x16x32_bf16 v[10:13], v[160:163], v[196:199], 0
	v_mfma_f32_16x16x32_bf16 v[62:65], v[156:159], v[172:175], v[62:65]
	v_mfma_f32_16x16x32_bf16 v[58:61], v[164:167], v[172:175], v[58:61]
	v_mfma_f32_16x16x32_bf16 v[50:53], v[156:159], v[184:187], v[50:53]
	v_mfma_f32_16x16x32_bf16 v[42:45], v[164:167], v[184:187], v[42:45]
	v_mfma_f32_16x16x32_bf16 v[34:37], v[156:159], v[192:195], v[34:37]
	v_mfma_f32_16x16x32_bf16 v[26:29], v[164:167], v[192:195], v[26:29]
	v_mfma_f32_16x16x32_bf16 v[18:21], v[156:159], v[200:203], v[18:21]
	v_mfma_f32_16x16x32_bf16 v[10:13], v[164:167], v[200:203], v[10:13]
	s_setprio 0
	s_barrier
	s_add_u32 s56, s18, 0xb0000
	s_addc_u32 s57, s19, 0
	s_add_i32 s55, s42, s27
	v_lshl_add_u64 v[152:153], s[56:57], 0, v[134:135]
	s_mov_b32 m0, s55
	s_nop 0
	global_load_lds_dwordx4 v[152:153], off
	v_lshl_add_u64 v[152:153], s[56:57], 0, v[136:137]
	s_add_i32 m0, s55, 0x2000
	s_nop 0
	global_load_lds_dwordx4 v[152:153], off
	s_waitcnt vmcnt(6)
	s_barrier
	s_setprio 1
	v_mfma_f32_16x16x32_bf16 v[54:57], v[206:209], v[168:171], 0
	v_mfma_f32_16x16x32_bf16 v[46:49], v[216:219], v[168:171], 0
	v_mfma_f32_16x16x32_bf16 v[38:41], v[206:209], v[180:183], 0
	v_mfma_f32_16x16x32_bf16 v[30:33], v[216:219], v[180:183], 0
	v_mfma_f32_16x16x32_bf16 v[22:25], v[206:209], v[188:191], 0
	v_mfma_f32_16x16x32_bf16 v[14:17], v[216:219], v[188:191], 0
	v_mfma_f32_16x16x32_bf16 v[6:9], v[206:209], v[196:199], 0
	v_mfma_f32_16x16x32_bf16 v[2:5], v[216:219], v[196:199], 0
	v_mfma_f32_16x16x32_bf16 v[54:57], v[212:215], v[172:175], v[54:57]
	v_mfma_f32_16x16x32_bf16 v[46:49], v[220:223], v[172:175], v[46:49]
	v_mfma_f32_16x16x32_bf16 v[38:41], v[212:215], v[184:187], v[38:41]
	v_mfma_f32_16x16x32_bf16 v[30:33], v[220:223], v[184:187], v[30:33]
	v_mfma_f32_16x16x32_bf16 v[22:25], v[212:215], v[192:195], v[22:25]
	v_mfma_f32_16x16x32_bf16 v[14:17], v[220:223], v[192:195], v[14:17]
	v_mfma_f32_16x16x32_bf16 v[6:9], v[212:215], v[200:203], v[6:9]
	v_mfma_f32_16x16x32_bf16 v[2:5], v[220:223], v[200:203], v[2:5]
	s_setprio 0
	s_add_i32 s55, 0, 0x18000
	v_add_u32_e32 v164, s55, v148
	s_barrier
	ds_read_b128 v[152:155], v164
	ds_read_b128 v[156:159], v164 offset:1024
	ds_read_b128 v[160:163], v164 offset:2048
	ds_read_b128 v[164:167], v164 offset:3072
	s_add_u32 s20, s20, 0xb0000
	s_addc_u32 s21, s21, 0
	s_mov_b32 m0, s33
	v_lshl_add_u64 v[206:207], s[20:21], 0, v[130:131]
	ds_read_b128 v[168:171], v150 offset:32768
	ds_read_b128 v[172:175], v150 offset:33792
	ds_read_b128 v[180:183], v150 offset:34816
	ds_read_b128 v[184:187], v150 offset:35840
	ds_read_b128 v[188:191], v150 offset:36864
	ds_read_b128 v[192:195], v150 offset:37888
	ds_read_b128 v[196:199], v150 offset:38912
	ds_read_b128 v[200:203], v150 offset:39936
	global_load_lds_dwordx4 v[206:207], off
	v_lshl_add_u64 v[206:207], s[20:21], 0, v[132:133]
	s_mov_b32 m0, s34
	s_nop 0
	global_load_lds_dwordx4 v[206:207], off
	s_waitcnt lgkmcnt(8)
	s_barrier
	s_waitcnt lgkmcnt(0)
	s_setprio 1
	s_waitcnt lgkmcnt(0)
	v_mfma_f32_16x16x32_bf16 v[126:129], v[152:155], v[168:171], v[126:129]
	v_mfma_f32_16x16x32_bf16 v[122:125], v[160:163], v[168:171], v[122:125]
	v_mfma_f32_16x16x32_bf16 v[114:117], v[152:155], v[180:183], v[114:117]
	v_mfma_f32_16x16x32_bf16 v[106:109], v[160:163], v[180:183], v[106:109]
	v_mfma_f32_16x16x32_bf16 v[98:101], v[152:155], v[188:191], v[98:101]
	v_mfma_f32_16x16x32_bf16 v[90:93], v[160:163], v[188:191], v[90:93]
	v_mfma_f32_16x16x32_bf16 v[82:85], v[152:155], v[196:199], v[82:85]
	v_mfma_f32_16x16x32_bf16 v[74:77], v[160:163], v[196:199], v[74:77]
	v_mfma_f32_16x16x32_bf16 v[126:129], v[156:159], v[172:175], v[126:129]
	v_mfma_f32_16x16x32_bf16 v[122:125], v[164:167], v[172:175], v[122:125]
	v_mfma_f32_16x16x32_bf16 v[114:117], v[156:159], v[184:187], v[114:117]
	v_mfma_f32_16x16x32_bf16 v[106:109], v[164:167], v[184:187], v[106:109]
	v_mfma_f32_16x16x32_bf16 v[98:101], v[156:159], v[192:195], v[98:101]
	v_mfma_f32_16x16x32_bf16 v[90:93], v[164:167], v[192:195], v[90:93]
	v_mfma_f32_16x16x32_bf16 v[82:85], v[156:159], v[200:203], v[82:85]
	v_mfma_f32_16x16x32_bf16 v[74:77], v[164:167], v[200:203], v[74:77]
	s_setprio 0
	s_barrier
	s_add_i32 s20, 0, 0x1c000
	s_add_i32 s21, s55, s27
	v_add_u32_e32 v179, s20, v148
	v_lshl_add_u64 v[146:147], v[146:147], 0, s[14:15]
	s_mov_b32 m0, s21
	ds_read_b128 v[206:209], v179
	ds_read_b128 v[212:215], v179 offset:1024
	ds_read_b128 v[216:219], v179 offset:2048
	ds_read_b128 v[220:223], v179 offset:3072
	global_load_lds_dwordx4 v[146:147], off
	v_lshl_add_u64 v[146:147], v[176:177], 0, s[14:15]
	s_add_i32 m0, s21, 0x2000
	s_nop 0
	global_load_lds_dwordx4 v[146:147], off
	s_barrier
	s_waitcnt lgkmcnt(0)
	s_setprio 1
	s_waitcnt lgkmcnt(0)
	v_mfma_f32_16x16x32_bf16 v[118:121], v[206:209], v[168:171], v[118:121]
	v_mfma_f32_16x16x32_bf16 v[110:113], v[216:219], v[168:171], v[110:113]
	v_mfma_f32_16x16x32_bf16 v[102:105], v[206:209], v[180:183], v[102:105]
	v_mfma_f32_16x16x32_bf16 v[94:97], v[216:219], v[180:183], v[94:97]
	v_mfma_f32_16x16x32_bf16 v[86:89], v[206:209], v[188:191], v[86:89]
	v_mfma_f32_16x16x32_bf16 v[78:81], v[216:219], v[188:191], v[78:81]
	v_mfma_f32_16x16x32_bf16 v[70:73], v[206:209], v[196:199], v[70:73]
	v_mfma_f32_16x16x32_bf16 v[66:69], v[216:219], v[196:199], v[66:69]
	v_mfma_f32_16x16x32_bf16 v[118:121], v[212:215], v[172:175], v[118:121]
	v_mfma_f32_16x16x32_bf16 v[110:113], v[220:223], v[172:175], v[110:113]
	v_mfma_f32_16x16x32_bf16 v[102:105], v[212:215], v[184:187], v[102:105]
	v_mfma_f32_16x16x32_bf16 v[94:97], v[220:223], v[184:187], v[94:97]
	v_mfma_f32_16x16x32_bf16 v[86:89], v[212:215], v[192:195], v[86:89]
	v_mfma_f32_16x16x32_bf16 v[78:81], v[220:223], v[192:195], v[78:81]
	v_mfma_f32_16x16x32_bf16 v[70:73], v[212:215], v[200:203], v[70:73]
	v_mfma_f32_16x16x32_bf16 v[66:69], v[220:223], v[200:203], v[66:69]
	s_setprio 0
	s_mov_b32 m0, s37
	v_lshl_add_u64 v[146:147], v[224:225], 0, s[14:15]
	s_barrier
	ds_read_b128 v[168:171], v150 offset:49152
	ds_read_b128 v[172:175], v150 offset:50176
	ds_read_b128 v[180:183], v150 offset:51200
	ds_read_b128 v[184:187], v150 offset:52224
	ds_read_b128 v[188:191], v150 offset:53248
	ds_read_b128 v[192:195], v150 offset:54272
	ds_read_b128 v[196:199], v150 offset:55296
	ds_read_b128 v[200:203], v150 offset:56320
	global_load_lds_dwordx4 v[146:147], off
	v_lshl_add_u64 v[146:147], v[226:227], 0, s[14:15]
	s_mov_b32 m0, s38
	s_nop 0
	global_load_lds_dwordx4 v[146:147], off
	s_barrier
	s_waitcnt lgkmcnt(0)
	s_setprio 1
	s_waitcnt lgkmcnt(0)
	v_mfma_f32_16x16x32_bf16 v[62:65], v[152:155], v[168:171], v[62:65]
	v_mfma_f32_16x16x32_bf16 v[58:61], v[160:163], v[168:171], v[58:61]
	v_mfma_f32_16x16x32_bf16 v[50:53], v[152:155], v[180:183], v[50:53]
	v_mfma_f32_16x16x32_bf16 v[42:45], v[160:163], v[180:183], v[42:45]
	v_mfma_f32_16x16x32_bf16 v[34:37], v[152:155], v[188:191], v[34:37]
	v_mfma_f32_16x16x32_bf16 v[26:29], v[160:163], v[188:191], v[26:29]
	v_mfma_f32_16x16x32_bf16 v[18:21], v[152:155], v[196:199], v[18:21]
	v_mfma_f32_16x16x32_bf16 v[10:13], v[160:163], v[196:199], v[10:13]
	v_mfma_f32_16x16x32_bf16 v[62:65], v[156:159], v[172:175], v[62:65]
	v_mfma_f32_16x16x32_bf16 v[58:61], v[164:167], v[172:175], v[58:61]
	v_mfma_f32_16x16x32_bf16 v[50:53], v[156:159], v[184:187], v[50:53]
	v_mfma_f32_16x16x32_bf16 v[42:45], v[164:167], v[184:187], v[42:45]
	v_mfma_f32_16x16x32_bf16 v[34:37], v[156:159], v[192:195], v[34:37]
	v_mfma_f32_16x16x32_bf16 v[26:29], v[164:167], v[192:195], v[26:29]
	v_mfma_f32_16x16x32_bf16 v[18:21], v[156:159], v[200:203], v[18:21]
	v_mfma_f32_16x16x32_bf16 v[10:13], v[164:167], v[200:203], v[10:13]
	s_setprio 0
	s_barrier
	s_add_u32 s18, s18, 0xb0080
	s_addc_u32 s19, s19, 0
	s_add_i32 s20, s20, s27
	v_lshl_add_u64 v[146:147], s[18:19], 0, v[134:135]
	s_mov_b32 m0, s20
	s_nop 0
	global_load_lds_dwordx4 v[146:147], off
	v_lshl_add_u64 v[146:147], s[18:19], 0, v[136:137]
	s_add_i32 m0, s20, 0x2000
	s_nop 0
	global_load_lds_dwordx4 v[146:147], off
	s_waitcnt vmcnt(6)
	s_barrier
	s_setprio 1
	v_mfma_f32_16x16x32_bf16 v[54:57], v[206:209], v[168:171], v[54:57]
	v_mfma_f32_16x16x32_bf16 v[46:49], v[216:219], v[168:171], v[46:49]
	v_mfma_f32_16x16x32_bf16 v[38:41], v[206:209], v[180:183], v[38:41]
	v_mfma_f32_16x16x32_bf16 v[30:33], v[216:219], v[180:183], v[30:33]
	v_mfma_f32_16x16x32_bf16 v[22:25], v[206:209], v[188:191], v[22:25]
	v_mfma_f32_16x16x32_bf16 v[14:17], v[216:219], v[188:191], v[14:17]
	v_mfma_f32_16x16x32_bf16 v[6:9], v[206:209], v[196:199], v[6:9]
	v_mfma_f32_16x16x32_bf16 v[2:5], v[216:219], v[196:199], v[2:5]
	v_mfma_f32_16x16x32_bf16 v[54:57], v[212:215], v[172:175], v[54:57]
	v_mfma_f32_16x16x32_bf16 v[46:49], v[220:223], v[172:175], v[46:49]
	v_mfma_f32_16x16x32_bf16 v[38:41], v[212:215], v[184:187], v[38:41]
	v_mfma_f32_16x16x32_bf16 v[30:33], v[220:223], v[184:187], v[30:33]
	v_mfma_f32_16x16x32_bf16 v[22:25], v[212:215], v[192:195], v[22:25]
	v_mfma_f32_16x16x32_bf16 v[14:17], v[220:223], v[192:195], v[14:17]
	v_mfma_f32_16x16x32_bf16 v[6:9], v[212:215], v[200:203], v[6:9]
	v_mfma_f32_16x16x32_bf16 v[2:5], v[220:223], v[200:203], v[2:5]
	s_setprio 0
	s_add_i32 s54, s54, 2
	s_add_u32 s16, s16, 0x100
	s_addc_u32 s17, s17, 0
	s_add_u32 s52, s52, 0x100
	s_addc_u32 s53, s53, 0
	s_cmp_gt_u32 s54, 41
	s_barrier
	s_cbranch_scc1 .Lpeel_p10_exit

.Lpeel_p10_exit:
	v_mov_b32_e32 v146, v178
	v_mov_b32_e32 v152, v211
	s_lshl_b32 s16, s50, 8
	s_add_i32 s16, s16, s36
	v_add_u32_e32 v146, s16, v146
	s_lshl_b32 s16, s51, 8
	s_ashr_i32 s17, s16, 31
	v_lshlrev_b32_e32 v152, 3, v152
	v_ashrrev_i32_e32 v147, 31, v146
	v_ashrrev_i32_e32 v153, 31, v152
	s_or_b64 s[16:17], s[16:17], s[8:9]
	v_lshlrev_b64 v[146:147], 10, v[146:147]
	v_lshl_add_u64 v[152:153], s[16:17], 0, v[152:153]
	v_lshl_add_u64 v[146:147], v[152:153], 0, v[146:147]
	v_lshlrev_b64 v[176:177], 1, v[146:147]
	v_lshl_add_u64 v[146:147], s[10:11], 0, v[176:177]
	global_load_dwordx4 v[152:155], v[146:147], off
	global_load_dwordx4 v[156:159], v[146:147], off offset:256
	v_add_co_u32_e32 v164, vcc, s40, v146
	s_mov_b32 s51, s48
	s_nop 0
	v_addc_co_u32_e32 v165, vcc, 0, v147, vcc
	global_load_dwordx4 v[160:163], v[164:165], off
	s_nop 0
	global_load_dwordx4 v[164:167], v[164:165], off offset:256
	v_add_co_u32_e32 v172, vcc, s35, v146
	s_mov_b32 s50, s49
	s_nop 0
	v_addc_co_u32_e32 v173, vcc, 0, v147, vcc
	global_load_dwordx4 v[168:171], v[172:173], off
	s_nop 0
	global_load_dwordx4 v[172:175], v[172:173], off offset:256
	v_add_co_u32_e32 v184, vcc, s39, v146
	s_mov_b64 s[18:19], s[4:5]
	s_nop 0
	v_addc_co_u32_e32 v185, vcc, 0, v147, vcc
	global_load_dwordx4 v[180:183], v[184:185], off
	s_nop 0
	global_load_dwordx4 v[184:187], v[184:185], off offset:256
	s_mov_b64 s[16:17], s[2:3]
	s_waitcnt vmcnt(0)
	v_lshlrev_b32_e32 v188, 16, v152
	v_and_b32_e32 v189, 0xffff0000, v152
	v_lshlrev_b32_e32 v152, 16, v153
	v_and_b32_e32 v153, 0xffff0000, v153
	v_lshlrev_b32_e32 v190, 16, v154
	v_and_b32_e32 v191, 0xffff0000, v154
	v_lshlrev_b32_e32 v154, 16, v155
	v_and_b32_e32 v155, 0xffff0000, v155
	v_pk_add_f32 v[128:129], v[128:129], v[152:153]
	v_pk_add_f32 v[126:127], v[126:127], v[188:189]
	v_pk_add_f32 v[152:153], v[124:125], v[154:155]
	v_pk_add_f32 v[122:123], v[122:123], v[190:191]
	v_lshlrev_b32_e32 v192, 16, v156
	v_and_b32_e32 v193, 0xffff0000, v156
	v_lshlrev_b32_e32 v156, 16, v157
	v_and_b32_e32 v157, 0xffff0000, v157
	v_lshlrev_b32_e32 v194, 16, v158
	v_and_b32_e32 v195, 0xffff0000, v158
	v_lshlrev_b32_e32 v158, 16, v159
	v_and_b32_e32 v159, 0xffff0000, v159
	v_cvt_pk_bf16_f32 v124, v126, v127
	v_cvt_pk_bf16_f32 v125, v128, v129
	v_cvt_pk_bf16_f32 v126, v122, v123
	v_cvt_pk_bf16_f32 v127, v152, v153
	v_lshl_add_u64 v[122:123], s[12:13], 0, v[176:177]
	global_store_dwordx4 v[122:123], v[124:127], off
	v_pk_add_f32 v[120:121], v[120:121], v[156:157]
	v_pk_add_f32 v[118:119], v[118:119], v[192:193]
	v_pk_add_f32 v[124:125], v[112:113], v[158:159]
	v_pk_add_f32 v[112:113], v[110:111], v[194:195]
	v_lshlrev_b32_e32 v196, 16, v160
	v_and_b32_e32 v197, 0xffff0000, v160
	v_lshlrev_b32_e32 v160, 16, v161
	v_and_b32_e32 v161, 0xffff0000, v161
	v_cvt_pk_bf16_f32 v110, v118, v119
	v_cvt_pk_bf16_f32 v111, v120, v121
	v_cvt_pk_bf16_f32 v112, v112, v113
	v_cvt_pk_bf16_f32 v113, v124, v125
	v_lshlrev_b32_e32 v198, 16, v162
	v_and_b32_e32 v199, 0xffff0000, v162
	v_lshlrev_b32_e32 v162, 16, v163
	v_and_b32_e32 v163, 0xffff0000, v163
	global_store_dwordx4 v[122:123], v[110:113], off offset:256
	v_lshlrev_b32_e32 v200, 16, v164
	v_and_b32_e32 v201, 0xffff0000, v164
	v_pk_add_f32 v[110:111], v[116:117], v[160:161]
	v_pk_add_f32 v[112:113], v[114:115], v[196:197]
	v_pk_add_f32 v[114:115], v[108:109], v[162:163]
	v_pk_add_f32 v[108:109], v[106:107], v[198:199]
	v_cvt_pk_bf16_f32 v107, v110, v111
	v_add_co_u32_e32 v110, vcc, s40, v122
	v_lshlrev_b32_e32 v164, 16, v165
	v_and_b32_e32 v165, 0xffff0000, v165
	v_lshlrev_b32_e32 v202, 16, v166
	v_and_b32_e32 v203, 0xffff0000, v166
	v_lshlrev_b32_e32 v166, 16, v167
	v_and_b32_e32 v167, 0xffff0000, v167
	v_cvt_pk_bf16_f32 v106, v112, v113
	v_cvt_pk_bf16_f32 v108, v108, v109
	v_cvt_pk_bf16_f32 v109, v114, v115
	v_addc_co_u32_e32 v111, vcc, 0, v123, vcc
	global_store_dwordx4 v[110:111], v[106:109], off
	v_pk_add_f32 v[104:105], v[104:105], v[164:165]
	v_pk_add_f32 v[102:103], v[102:103], v[200:201]
	v_pk_add_f32 v[106:107], v[96:97], v[166:167]
	v_pk_add_f32 v[96:97], v[94:95], v[202:203]
	v_lshlrev_b32_e32 v206, 16, v168
	v_and_b32_e32 v207, 0xffff0000, v168
	v_lshlrev_b32_e32 v168, 16, v169
	v_and_b32_e32 v169, 0xffff0000, v169
	v_cvt_pk_bf16_f32 v94, v102, v103
	v_cvt_pk_bf16_f32 v95, v104, v105
	v_cvt_pk_bf16_f32 v96, v96, v97
	v_cvt_pk_bf16_f32 v97, v106, v107
	v_lshlrev_b32_e32 v208, 16, v170
	v_and_b32_e32 v209, 0xffff0000, v170
	v_lshlrev_b32_e32 v170, 16, v171
	v_and_b32_e32 v171, 0xffff0000, v171
	global_store_dwordx4 v[110:111], v[94:97], off offset:256
	v_lshlrev_b32_e32 v212, 16, v172
	v_and_b32_e32 v213, 0xffff0000, v172
	v_pk_add_f32 v[94:95], v[100:101], v[168:169]
	v_pk_add_f32 v[96:97], v[98:99], v[206:207]
	v_pk_add_f32 v[98:99], v[92:93], v[170:171]
	v_pk_add_f32 v[92:93], v[90:91], v[208:209]
	v_cvt_pk_bf16_f32 v91, v94, v95
	v_add_co_u32_e32 v94, vcc, s35, v122
	v_lshlrev_b32_e32 v172, 16, v173
	v_and_b32_e32 v173, 0xffff0000, v173
	v_lshlrev_b32_e32 v214, 16, v174
	v_and_b32_e32 v215, 0xffff0000, v174
	v_lshlrev_b32_e32 v174, 16, v175
	v_and_b32_e32 v175, 0xffff0000, v175
	v_cvt_pk_bf16_f32 v90, v96, v97
	v_cvt_pk_bf16_f32 v92, v92, v93
	v_cvt_pk_bf16_f32 v93, v98, v99
	v_addc_co_u32_e32 v95, vcc, 0, v123, vcc
	global_store_dwordx4 v[94:95], v[90:93], off
	v_pk_add_f32 v[88:89], v[88:89], v[172:173]
	v_pk_add_f32 v[86:87], v[86:87], v[212:213]
	v_pk_add_f32 v[90:91], v[80:81], v[174:175]
	v_pk_add_f32 v[80:81], v[78:79], v[214:215]
	v_lshlrev_b32_e32 v216, 16, v180
	v_and_b32_e32 v217, 0xffff0000, v180
	v_lshlrev_b32_e32 v180, 16, v181
	v_and_b32_e32 v181, 0xffff0000, v181
	v_cvt_pk_bf16_f32 v78, v86, v87
	v_cvt_pk_bf16_f32 v79, v88, v89
	v_cvt_pk_bf16_f32 v80, v80, v81
	v_cvt_pk_bf16_f32 v81, v90, v91
	v_lshlrev_b32_e32 v218, 16, v182
	v_and_b32_e32 v219, 0xffff0000, v182
	v_lshlrev_b32_e32 v182, 16, v183
	v_and_b32_e32 v183, 0xffff0000, v183
	global_store_dwordx4 v[94:95], v[78:81], off offset:256
	v_lshlrev_b32_e32 v220, 16, v184
	v_and_b32_e32 v221, 0xffff0000, v184
	v_pk_add_f32 v[78:79], v[84:85], v[180:181]
	v_pk_add_f32 v[80:81], v[82:83], v[216:217]
	v_pk_add_f32 v[82:83], v[76:77], v[182:183]
	v_pk_add_f32 v[76:77], v[74:75], v[218:219]
	v_cvt_pk_bf16_f32 v75, v78, v79
	v_add_co_u32_e32 v78, vcc, s39, v122
	v_lshlrev_b32_e32 v184, 16, v185
	v_and_b32_e32 v185, 0xffff0000, v185
	v_lshlrev_b32_e32 v222, 16, v186
	v_and_b32_e32 v223, 0xffff0000, v186
	v_lshlrev_b32_e32 v186, 16, v187
	v_and_b32_e32 v187, 0xffff0000, v187
	v_cvt_pk_bf16_f32 v74, v80, v81
	v_cvt_pk_bf16_f32 v76, v76, v77
	v_cvt_pk_bf16_f32 v77, v82, v83
	v_addc_co_u32_e32 v79, vcc, 0, v123, vcc
	global_store_dwordx4 v[78:79], v[74:77], off
	v_pk_add_f32 v[72:73], v[72:73], v[184:185]
	v_pk_add_f32 v[70:71], v[70:71], v[220:221]
	v_pk_add_f32 v[74:75], v[68:69], v[186:187]
	v_pk_add_f32 v[68:69], v[66:67], v[222:223]
	v_cvt_pk_bf16_f32 v66, v70, v71
	v_cvt_pk_bf16_f32 v67, v72, v73
	v_cvt_pk_bf16_f32 v68, v68, v69
	v_cvt_pk_bf16_f32 v69, v74, v75
	global_store_dwordx4 v[78:79], v[66:69], off offset:256
	v_add_co_u32_e32 v70, vcc, s43, v146
	s_nop 1
	v_addc_co_u32_e32 v71, vcc, 0, v147, vcc
	global_load_dwordx4 v[66:69], v[70:71], off
	s_nop 0
	global_load_dwordx4 v[70:73], v[70:71], off offset:256
	v_add_co_u32_e32 v78, vcc, s44, v146
	s_waitcnt vmcnt(0)
	v_lshlrev_b32_e32 v98, 16, v66
	v_addc_co_u32_e32 v79, vcc, 0, v147, vcc
	global_load_dwordx4 v[74:77], v[78:79], off
	s_nop 0
	global_load_dwordx4 v[78:81], v[78:79], off offset:256
	v_add_co_u32_e32 v86, vcc, s45, v146
	v_and_b32_e32 v99, 0xffff0000, v66
	s_nop 0
	v_addc_co_u32_e32 v87, vcc, 0, v147, vcc
	global_load_dwordx4 v[82:85], v[86:87], off
	s_nop 0
	global_load_dwordx4 v[86:89], v[86:87], off offset:256
	v_add_co_u32_e32 v94, vcc, s46, v146
	v_lshlrev_b32_e32 v66, 16, v67
	s_nop 0
	v_addc_co_u32_e32 v95, vcc, 0, v147, vcc
	global_load_dwordx4 v[90:93], v[94:95], off
	s_nop 0
	global_load_dwordx4 v[94:97], v[94:95], off offset:256
	v_and_b32_e32 v67, 0xffff0000, v67
	v_lshlrev_b32_e32 v100, 16, v68
	v_and_b32_e32 v101, 0xffff0000, v68
	v_lshlrev_b32_e32 v68, 16, v69
	v_and_b32_e32 v69, 0xffff0000, v69
	v_pk_add_f32 v[62:63], v[62:63], v[98:99]
	v_pk_add_f32 v[64:65], v[64:65], v[66:67]
	v_pk_add_f32 v[66:67], v[60:61], v[68:69]
	v_pk_add_f32 v[60:61], v[58:59], v[100:101]
	v_cvt_pk_bf16_f32 v58, v62, v63
	v_add_co_u32_e32 v62, vcc, s43, v122
	v_lshlrev_b32_e32 v102, 16, v70
	v_and_b32_e32 v103, 0xffff0000, v70
	v_lshlrev_b32_e32 v70, 16, v71
	v_and_b32_e32 v71, 0xffff0000, v71
	v_lshlrev_b32_e32 v104, 16, v72
	v_and_b32_e32 v105, 0xffff0000, v72
	v_lshlrev_b32_e32 v72, 16, v73
	v_and_b32_e32 v73, 0xffff0000, v73
	v_cvt_pk_bf16_f32 v59, v64, v65
	v_cvt_pk_bf16_f32 v60, v60, v61
	v_cvt_pk_bf16_f32 v61, v66, v67
	v_addc_co_u32_e32 v63, vcc, 0, v123, vcc
	global_store_dwordx4 v[62:63], v[58:61], off
	v_pk_add_f32 v[56:57], v[56:57], v[70:71]
	v_pk_add_f32 v[54:55], v[54:55], v[102:103]
	v_pk_add_f32 v[58:59], v[48:49], v[72:73]
	v_pk_add_f32 v[48:49], v[46:47], v[104:105]
	v_cvt_pk_bf16_f32 v46, v54, v55
	v_cvt_pk_bf16_f32 v47, v56, v57
	v_cvt_pk_bf16_f32 v48, v48, v49
	v_cvt_pk_bf16_f32 v49, v58, v59
	global_store_dwordx4 v[62:63], v[46:49], off offset:256
	s_waitcnt vmcnt(0)
	v_lshlrev_b32_e32 v106, 16, v74
	v_and_b32_e32 v107, 0xffff0000, v74
	v_lshlrev_b32_e32 v74, 16, v75
	v_and_b32_e32 v75, 0xffff0000, v75
	v_lshlrev_b32_e32 v108, 16, v76
	v_and_b32_e32 v109, 0xffff0000, v76
	v_lshlrev_b32_e32 v76, 16, v77
	v_and_b32_e32 v77, 0xffff0000, v77
	v_pk_add_f32 v[46:47], v[52:53], v[74:75]
	v_pk_add_f32 v[48:49], v[50:51], v[106:107]
	v_pk_add_f32 v[50:51], v[44:45], v[76:77]
	v_pk_add_f32 v[44:45], v[42:43], v[108:109]
	v_cvt_pk_bf16_f32 v43, v46, v47
	v_add_co_u32_e32 v46, vcc, s44, v122
	v_lshlrev_b32_e32 v110, 16, v78
	v_and_b32_e32 v111, 0xffff0000, v78
	v_lshlrev_b32_e32 v78, 16, v79
	v_and_b32_e32 v79, 0xffff0000, v79
	v_lshlrev_b32_e32 v112, 16, v80
	v_and_b32_e32 v113, 0xffff0000, v80
	v_lshlrev_b32_e32 v80, 16, v81
	v_and_b32_e32 v81, 0xffff0000, v81
	v_cvt_pk_bf16_f32 v42, v48, v49
	v_cvt_pk_bf16_f32 v44, v44, v45
	v_cvt_pk_bf16_f32 v45, v50, v51
	v_addc_co_u32_e32 v47, vcc, 0, v123, vcc
	global_store_dwordx4 v[46:47], v[42:45], off
	v_pk_add_f32 v[40:41], v[40:41], v[78:79]
	v_pk_add_f32 v[38:39], v[38:39], v[110:111]
	v_pk_add_f32 v[42:43], v[32:33], v[80:81]
	v_pk_add_f32 v[32:33], v[30:31], v[112:113]
	v_lshlrev_b32_e32 v114, 16, v82
	v_and_b32_e32 v115, 0xffff0000, v82
	v_lshlrev_b32_e32 v82, 16, v83
	v_and_b32_e32 v83, 0xffff0000, v83
	v_cvt_pk_bf16_f32 v30, v38, v39
	v_cvt_pk_bf16_f32 v31, v40, v41
	v_cvt_pk_bf16_f32 v32, v32, v33
	v_cvt_pk_bf16_f32 v33, v42, v43
	v_lshlrev_b32_e32 v116, 16, v84
	v_and_b32_e32 v117, 0xffff0000, v84
	v_lshlrev_b32_e32 v84, 16, v85
	v_and_b32_e32 v85, 0xffff0000, v85
	global_store_dwordx4 v[46:47], v[30:33], off offset:256
	v_lshlrev_b32_e32 v118, 16, v86
	v_and_b32_e32 v119, 0xffff0000, v86
	v_pk_add_f32 v[30:31], v[36:37], v[82:83]
	v_pk_add_f32 v[32:33], v[34:35], v[114:115]
	v_pk_add_f32 v[34:35], v[28:29], v[84:85]
	v_pk_add_f32 v[28:29], v[26:27], v[116:117]
	v_cvt_pk_bf16_f32 v27, v30, v31
	v_add_co_u32_e32 v30, vcc, s45, v122
	v_lshlrev_b32_e32 v86, 16, v87
	v_and_b32_e32 v87, 0xffff0000, v87
	v_lshlrev_b32_e32 v120, 16, v88
	v_and_b32_e32 v121, 0xffff0000, v88
	v_lshlrev_b32_e32 v88, 16, v89
	v_and_b32_e32 v89, 0xffff0000, v89
	v_cvt_pk_bf16_f32 v26, v32, v33
	v_cvt_pk_bf16_f32 v28, v28, v29
	v_cvt_pk_bf16_f32 v29, v34, v35
	v_addc_co_u32_e32 v31, vcc, 0, v123, vcc
	global_store_dwordx4 v[30:31], v[26:29], off
	v_pk_add_f32 v[24:25], v[24:25], v[86:87]
	v_pk_add_f32 v[22:23], v[22:23], v[118:119]
	v_pk_add_f32 v[26:27], v[16:17], v[88:89]
	v_pk_add_f32 v[16:17], v[14:15], v[120:121]
	v_lshlrev_b32_e32 v124, 16, v90
	v_and_b32_e32 v125, 0xffff0000, v90
	v_lshlrev_b32_e32 v90, 16, v91
	v_and_b32_e32 v91, 0xffff0000, v91
	v_cvt_pk_bf16_f32 v14, v22, v23
	v_cvt_pk_bf16_f32 v15, v24, v25
	v_cvt_pk_bf16_f32 v16, v16, v17
	v_cvt_pk_bf16_f32 v17, v26, v27
	v_lshlrev_b32_e32 v126, 16, v92
	v_and_b32_e32 v127, 0xffff0000, v92
	v_lshlrev_b32_e32 v92, 16, v93
	v_and_b32_e32 v93, 0xffff0000, v93
	global_store_dwordx4 v[30:31], v[14:17], off offset:256
	v_lshlrev_b32_e32 v128, 16, v94
	v_and_b32_e32 v129, 0xffff0000, v94
	v_pk_add_f32 v[14:15], v[20:21], v[90:91]
	v_pk_add_f32 v[16:17], v[18:19], v[124:125]
	v_pk_add_f32 v[18:19], v[12:13], v[92:93]
	v_pk_add_f32 v[12:13], v[10:11], v[126:127]
	v_cvt_pk_bf16_f32 v11, v14, v15
	v_add_co_u32_e32 v14, vcc, s46, v122
	v_lshlrev_b32_e32 v94, 16, v95
	v_and_b32_e32 v95, 0xffff0000, v95
	v_lshlrev_b32_e32 v146, 16, v96
	v_and_b32_e32 v147, 0xffff0000, v96
	v_lshlrev_b32_e32 v96, 16, v97
	v_and_b32_e32 v97, 0xffff0000, v97
	v_cvt_pk_bf16_f32 v10, v16, v17
	v_cvt_pk_bf16_f32 v12, v12, v13
	v_cvt_pk_bf16_f32 v13, v18, v19
	v_addc_co_u32_e32 v15, vcc, 0, v123, vcc
	global_store_dwordx4 v[14:15], v[10:13], off
	v_pk_add_f32 v[8:9], v[8:9], v[94:95]
	v_pk_add_f32 v[6:7], v[6:7], v[128:129]
	v_pk_add_f32 v[10:11], v[4:5], v[96:97]
	v_pk_add_f32 v[4:5], v[2:3], v[146:147]
	v_cvt_pk_bf16_f32 v2, v6, v7
	v_cvt_pk_bf16_f32 v3, v8, v9
	v_cvt_pk_bf16_f32 v4, v4, v5
	v_cvt_pk_bf16_f32 v5, v10, v11
	global_store_dwordx4 v[14:15], v[2:5], off offset:256
	s_and_b64 vcc, exec, s[0:1]
	s_cbranch_vccz .LBB0_1186
	s_waitcnt vmcnt(0)
	s_cmpk_gt_u32 s26, 0xff
	s_cbranch_scc1 .LBB0_1201
	s_barrier
